# P0 sample rows moved from waves 0..511 to the odd (tile-less) waves of workgroups 0..127
# baseline (speedup 1.0000x reference)
.Lwt_done:
.LBB0_178:
	v_readlane_b32 s8, v253, 0
	v_readlane_b32 s10, v253, 2
	v_readlane_b32 s11, v253, 3
	s_add_u32 s46, s10, 0x3400000
	s_addc_u32 s47, s11, 0
	s_cmpk_lt_i32 s36, 0x4200
	s_cselect_b64 s[0:1], -1, 0
	v_readlane_b32 s9, v253, 1
	v_writelane_b32 v253, s0, 46
	s_cmpk_gt_i32 s36, 0x41ff
	v_mbcnt_lo_u32_b32 v42, -1, 0
	v_writelane_b32 v253, s1, 47
	s_cbranch_scc1 .LBB0_192
	v_mbcnt_hi_u32_b32 v3, -1, v42
	s_ashr_i32 s39, s38, 31
	v_lshlrev_b32_e32 v4, 4, v227
	v_lshlrev_b32_e32 v5, 3, v227
	v_mov_b32_e32 v12, 0
	v_xor_b32_e32 v6, 1, v227
	v_lshlrev_b32_e32 v6, 2, v6
	v_xor_b32_e32 v7, 2, v227
	v_lshlrev_b32_e32 v7, 2, v7
	v_xor_b32_e32 v8, 4, v227
	v_lshlrev_b32_e32 v8, 2, v8
	v_xor_b32_e32 v9, 8, v227
	v_lshlrev_b32_e32 v9, 2, v9
	v_xor_b32_e32 v10, 16, v227
	v_lshlrev_b32_e32 v10, 2, v10
	v_xor_b32_e32 v11, 32, v227
	v_lshlrev_b32_e32 v11, 2, v11
	v_readlane_b32 s48, v253, 26
	v_readlane_b32 s49, v253, 27
	v_readlane_b32 s50, v253, 28
	v_readlane_b32 s51, v253, 29
	v_readlane_b32 s52, v253, 44
	v_readlane_b32 s53, v253, 45
	s_mov_b32 s14, s36
	s_movk_i32 s98, 0x4200
	s_mov_b32 s99, s38
	s_cmpk_lg_u32 s78, 0x100
	s_cbranch_scc1 .Lxn_loop
	s_movk_i32 s98, 0x4000

.Lxn_done:
	s_cmpk_lg_u32 s98, 0x4000
	s_cbranch_scc1 .Lxn_fin
	s_bitcmp1_b32 s36, 0
	s_cbranch_scc0 .Lxn_fin
	s_cmpk_gt_u32 s36, 0x3ff
	s_cbranch_scc1 .Lxn_fin
	s_lshr_b32 s14, s36, 1
	s_addk_i32 s14, 0x4000
	s_add_i32 s98, s14, 1
	s_branch .Lxn_loop
